# mixer phases: waves 4-7 start ~1500 cycles late (stagger SIMD partners); remaining B-mixer Y stores sc1
# baseline (speedup 1.0000x reference)
.LBB0_191:
	s_and_b64 vcc, exec, s[16:17]
	s_cbranch_vccz .LBB0_230
	s_lshl_b32 s44, s75, 3
	s_cmp_gt_u32 s74, 13
	s_mov_b64 s[2:3], -1
	s_cbranch_scc0 .LBB0_210
	v_readlane_b32 s2, v242, 50
	v_readlane_b32 s3, v242, 51
	s_andn2_b64 vcc, exec, s[2:3]
	s_cbranch_vccnz .LBB0_209
	s_add_u32 s6, s26, 0x125fe000
	v_readlane_b32 s40, v241, 14
	s_addc_u32 s7, s27, 0
	s_mov_b32 s34, s40
	v_readlane_b32 s35, v241, 13
	v_readlane_b32 s86, v242, 42
	s_cmp_lt_u32 s86, 0x100
	s_cbranch_scc1 .Lstagger_b_done
	s_sleep 24
.Lstagger_b_done:
	s_branch .LBB0_197
.LBB0_195:
	v_ashrrev_i32_e32 v32, 2, v149
	v_and_b32_e32 v32, -8, v32
	s_nop 8
	v_cvt_pk_bf16_f32 v0, v0, v1
	v_cvt_pk_bf16_f32 v1, v2, v3
	v_lshlrev_b32_e32 v2, 4, v147
	v_add_u32_e32 v32, v168, v32
	v_cvt_pk_bf16_f32 v16, v16, v17
	v_cvt_pk_bf16_f32 v17, v18, v19
	v_and_b32_e32 v18, 0x70, v2
	v_add_u32_e32 v2, v32, v18
	ds_write_b64 v2, v[16:17]
	v_xad_u32 v2, v18, 64, v32
	ds_write_b64 v2, v[0:1]
	v_cvt_pk_bf16_f32 v0, v20, v21
	v_cvt_pk_bf16_f32 v1, v22, v23
	v_cvt_pk_bf16_f32 v2, v4, v5
	v_xad_u32 v4, v18, 16, v32
	s_movk_i32 s8, 0x50
	v_cvt_pk_bf16_f32 v3, v6, v7
	ds_write_b64 v4, v[0:1]
	v_xad_u32 v0, v18, s8, v32
	ds_write_b64 v0, v[2:3]
	v_cvt_pk_bf16_f32 v0, v24, v25
	v_cvt_pk_bf16_f32 v1, v26, v27
	v_xad_u32 v4, v18, 32, v32
	s_movk_i32 s8, 0x60
	v_cvt_pk_bf16_f32 v2, v8, v9
	v_cvt_pk_bf16_f32 v3, v10, v11
	ds_write_b64 v4, v[0:1]
	v_xad_u32 v0, v18, s8, v32
	ds_write_b64 v0, v[2:3]
	v_cvt_pk_bf16_f32 v0, v28, v29
	v_cvt_pk_bf16_f32 v1, v30, v31
	v_xad_u32 v4, v18, 48, v32
	s_movk_i32 s8, 0x70
	s_lshl_b64 s[2:3], s[24:25], 1
	v_cvt_pk_bf16_f32 v2, v12, v13
	v_cvt_pk_bf16_f32 v3, v14, v15
	ds_write_b64 v4, v[0:1]
	v_xad_u32 v0, v18, s8, v32
	s_add_u32 s2, s79, s2
	ds_write_b64 v0, v[2:3]
	s_addc_u32 s3, s80, s3
	ds_read_b128 v[2:5], v158
	s_add_u32 s2, s2, s16
	s_addc_u32 s3, s3, s17
	v_lshlrev_b32_e32 v158, 1, v146
	v_lshl_add_u64 v[0:1], s[2:3], 0, v[158:159]
	v_lshl_add_u64 v[6:7], v[0:1], 0, v[152:153]
	v_mov_b32_e32 v152, v144
	s_waitcnt lgkmcnt(0)
	global_store_dwordx4 v[6:7], v[2:5], off sc1
.LBB0_196:
	ds_read_b128 v[2:5], v151
	v_ashrrev_i32_e32 v149, 31, v148
	v_lshlrev_b64 v[6:7], 11, v[148:149]
	v_lshl_add_u64 v[6:7], v[0:1], 0, v[6:7]
	v_ashrrev_i32_e32 v151, 31, v150
	s_waitcnt lgkmcnt(0)
	global_store_dwordx4 v[6:7], v[2:5], off sc1
	v_add_u32_e32 v6, 16, v152
	v_ashrrev_i32_e32 v7, 31, v6
	v_lshlrev_b32_e32 v2, 7, v6
	v_add3_u32 v2, s33, v2, v145
	ds_read_b128 v[2:5], v2
	v_lshlrev_b64 v[6:7], 11, v[6:7]
	v_lshl_add_u64 v[6:7], v[0:1], 0, v[6:7]
	s_add_i32 s40, s40, s52
	s_add_i32 s35, s35, s52
	s_waitcnt lgkmcnt(0)
	global_store_dwordx4 v[6:7], v[2:5], off sc1
	ds_read_b128 v[2:5], v172
	v_lshlrev_b64 v[6:7], 11, v[150:151]
	s_add_i32 s34, s34, s52
	v_lshl_add_u64 v[0:1], v[0:1], 0, v[6:7]
	s_cmpk_lt_i32 s40, 0x2000
	s_waitcnt lgkmcnt(0)
	global_store_dwordx4 v[0:1], v[2:5], off sc1
	s_cbranch_scc0 .LBB0_209

.LBB0_210:
	s_andn2_b64 vcc, exec, s[2:3]
	s_cbranch_vccnz .LBB0_229
	v_readlane_b32 s2, v242, 52
	v_readlane_b32 s3, v242, 53
	s_andn2_b64 vcc, exec, s[2:3]
	s_cbranch_vccnz .LBB0_229
	s_lshl_b32 s3, s75, 17
	s_mul_i32 s2, s75, 0x300
	s_add_u32 s45, s60, s3
	s_addc_u32 s46, s61, 0
	s_lshl_b32 s47, s2, 2
	v_readlane_b32 s48, v241, 15
	v_readlane_b32 s49, v241, 14
	v_readlane_b32 s86, v242, 42
	s_cmp_lt_u32 s86, 0x100
	s_cbranch_scc1 .Lstagger_a_done
	s_sleep 24
